# MLA: K fragments of half 0 requested before the global prefetch at the tile top; otherwise as previous
# speedup vs baseline: 1.0160x; 1.0003x over previous
; #define ATT_ISSUE(kt) do { kreg0 = *(const u32x4*)(Kg + (size_t)((kt) * 64 + kr0) * ldk + kc0 * 8); \
;         if (has1) kreg1 = *(const u32x4*)(Kg + (size_t)((kt) * 64 + kr1) * ldk + kc1 * 8); \
;         vreg = *(const u32x4*)(Vtg + (size_t)ve * TB + (kt) * 64 + vc * 8); } while (0)
; template <int DQK, bool MASK, int NQ>
; __device__ __forceinline__ void attn_unit(unsigned char* lds, const bf16_t* Qg, int ldq, const bf16_t* Kg, int ldk, const bf16_t* Vtg, bf16_t* Og, int ldo,
;                                           int qi0, int a0, int n1, int b0, int n2, float m0, bool sink) {
;     ...
;     { const int kt0 = ATT_TILE(0); ATT_ISSUE(kt0); ATT_COMMIT(0); }
;     __syncthreads();
; #pragma unroll 1
;     for (int tt = 0; tt < nt; ++tt) {
;         const int kt = ATT_TILE(tt);
;         if (tt + 1 < nt) { const int ktn = ATT_TILE(tt + 1); ATT_ISSUE(ktn); }
;         if (!ATT_SKIP(kt)) {
; #pragma unroll 1
;           for (int hb = 0; hb < 2; ++hb) {
;             f32x4 sc[2][NQ];
;             { const unsigned char* kb_ = lds + KOFF + (tt & 1) * KBYTES + hb * 512 + g * 1024 + ql * 16;
;               __builtin_amdgcn_s_setprio(1);
; #pragma unroll
;               for (int k2 = 0; k2 < 2; ++k2) {
; #pragma unroll
;                   for (int c = 0; c < NC; ++c) {
;                       const bf16x8 kf = *(const bf16x8*)(kb_ + c * 4096 + k2 * 256);
; #pragma unroll
;                       for (int qb = 0; qb < NQ; ++qb) sc[k2][qb] = __builtin_amdgcn_mfma_f32_16x16x32_bf16(kf, qf[qb][c], c == 0 ? negm[qb] : sc[k2][qb], 0, 0, 0);
;                   } }
;               __builtin_amdgcn_s_setprio(0); }
.Lmla_tile:
	s_and_b32 s0, s13, 1
	s_mul_i32 s1, s0, 0x3000
	s_mulk_i32 s0, 0x2400
	v_add_u32_e32 v37, s1, v250
	v_add_u32_e32 v38, s0, v251
	ds_read_b128 v[196:199], v37
	ds_read_b128 v[192:195], v37 offset:4096
	ds_read_b128 v[188:191], v37 offset:8192
	ds_read_b128 v[184:187], v37 offset:256
	ds_read_b128 v[242:245], v37 offset:4352
	ds_read_b128 v[246:249], v37 offset:8448
	s_add_i32 s24, s13, 1
	s_cmp_ge_i32 s24, s19
	s_cbranch_scc1 .Lmla_noload
	v_mov_b32_e32 v232, s24
	v_lshlrev_b32_e32 v234, 6, v232
	v_or_b32_e32 v232, v234, v43
	s_movk_i32 s0, 0x600
	v_mov_b64_e32 v[140:141], s[2:3]
	s_nop 0
	v_mad_i64_i32 v[148:149], s[0:1], v232, s0, v[140:141]
	v_lshl_add_u64 v[140:141], v[210:211], 1, v[148:149]
	global_load_dwordx4 v[140:143], v[140:141], off
	s_and_saveexec_b64 s[0:1], s[38:39]
	s_cbranch_execz .Lmla_nok1
	v_lshl_add_u64 v[144:145], v[212:213], 1, v[148:149]
	global_load_dwordx4 v[144:147], v[144:145], off
.Lmla_nok1:
	s_or_b64 exec, exec, s[0:1]
	v_ashrrev_i32_e32 v235, 31, v234
	v_lshl_add_u64 v[234:235], v[234:235], 1, v[214:215]
	global_load_dwordx4 v[148:151], v[234:235], off
.Lmla_noload:
	s_waitcnt lgkmcnt(5)
	v_mfma_f32_16x16x32_bf16 v[180:183], v[196:199], v[92:95], v[160:163]
	v_mfma_f32_16x16x32_bf16 v[176:179], v[196:199], v[104:107], v[156:159]
	v_mfma_f32_16x16x32_bf16 v[172:175], v[196:199], v[116:119], v[152:155]
	v_mfma_f32_16x16x32_bf16 v[168:171], v[196:199], v[128:131], v[164:167]
	s_waitcnt lgkmcnt(4)
	v_mfma_f32_16x16x32_bf16 v[180:183], v[192:195], v[96:99], v[180:183]
	v_mfma_f32_16x16x32_bf16 v[176:179], v[192:195], v[108:111], v[176:179]
	v_mfma_f32_16x16x32_bf16 v[172:175], v[192:195], v[120:123], v[172:175]
	v_mfma_f32_16x16x32_bf16 v[168:171], v[192:195], v[132:135], v[168:171]
	s_waitcnt lgkmcnt(3)
	v_mfma_f32_16x16x32_bf16 v[180:183], v[188:191], v[100:103], v[180:183]
	v_mfma_f32_16x16x32_bf16 v[176:179], v[188:191], v[112:115], v[176:179]
	v_mfma_f32_16x16x32_bf16 v[172:175], v[188:191], v[124:127], v[172:175]
	v_mfma_f32_16x16x32_bf16 v[168:171], v[188:191], v[136:139], v[168:171]
	s_waitcnt lgkmcnt(2)
	v_mfma_f32_16x16x32_bf16 v[196:199], v[184:187], v[92:95], v[160:163]
	v_mfma_f32_16x16x32_bf16 v[192:195], v[184:187], v[104:107], v[156:159]
	v_mfma_f32_16x16x32_bf16 v[188:191], v[184:187], v[116:119], v[152:155]
	v_mfma_f32_16x16x32_bf16 v[184:187], v[184:187], v[128:131], v[164:167]
	s_waitcnt lgkmcnt(1)
	v_mfma_f32_16x16x32_bf16 v[196:199], v[242:245], v[96:99], v[196:199]
	v_mfma_f32_16x16x32_bf16 v[192:195], v[242:245], v[108:111], v[192:195]
	v_max_f32_e32 v216, v180, v181
	v_mfma_f32_16x16x32_bf16 v[188:191], v[242:245], v[120:123], v[188:191]
	v_max_f32_e32 v217, v176, v177
	v_mfma_f32_16x16x32_bf16 v[184:187], v[242:245], v[132:135], v[184:187]
	v_max_f32_e32 v218, v172, v173
	s_waitcnt lgkmcnt(0)
	v_mfma_f32_16x16x32_bf16 v[196:199], v[246:249], v[100:103], v[196:199]
	v_max_f32_e32 v219, v168, v169
	v_mfma_f32_16x16x32_bf16 v[192:195], v[246:249], v[112:115], v[192:195]
	v_max3_f32 v216, v216, v182, v183
	v_mfma_f32_16x16x32_bf16 v[188:191], v[246:249], v[124:127], v[188:191]
	v_max3_f32 v217, v217, v178, v179
	v_mfma_f32_16x16x32_bf16 v[184:187], v[246:249], v[136:139], v[184:187]
	v_max3_f32 v218, v218, v174, v175
	ds_read_b128 v[232:235], v37 offset:512
	ds_read_b128 v[44:47], v37 offset:4608
	ds_read_b128 v[200:203], v37 offset:8704
	ds_read_b128 v[236:239], v37 offset:768
	ds_read_b128 v[242:245], v37 offset:4864
	ds_read_b128 v[246:249], v37 offset:8960
	v_max3_f32 v219, v219, v170, v171
	v_max3_f32 v216, v216, v196, v197
	v_max3_f32 v217, v217, v192, v193
	v_max3_f32 v218, v218, v188, v189
	v_max3_f32 v219, v219, v184, v185
	v_max3_f32 v216, v216, v198, v199
	v_max3_f32 v217, v217, v194, v195
	v_max3_f32 v218, v218, v190, v191
	v_max3_f32 v219, v219, v186, v187
	v_max3_f32 v220, v216, v217, v218
	v_max_f32_e32 v220, v220, v219
	v_cmp_lt_f32_e32 vcc, 4.0, v220
	s_or_b64 s[0:1], s[10:11], vcc
	s_cmp_lg_u64 s[0:1], 0
	s_cbranch_scc1 .Lmla_rare_a
